# prompt attention loop: the end-of-half K/V staging (wait + ds_write to the LDS rings) is issued inside the compute block before the last three MFMAs, so its LDS latency hides behind them; the original
# speedup vs baseline: 1.0114x; 1.0114x over previous
.LBB0_548:
	s_cmp_gt_u32 s52, s51
	s_mul_i32 s61, s25, 0x2200
	s_cbranch_scc1 .LBB0_550
	s_and_b32 s42, s52, 2
	s_mulk_i32 s42, 0x3400
	v_add_u32_e32 v0, s42, v160
	v_add_u32_e32 v242, s61, v161
	v_add_u32_e32 v163, 0xe000, v242
	v_add_u32_e32 v242, 0xd000, v242
	ds_read_b128 v[82:85], v0 offset:13312
	ds_read_b128 v[98:101], v0 offset:19968
	ds_read_b128 v[164:167], v0 offset:13344
	ds_read_b128 v[168:171], v0 offset:20000
	ds_read2_b64 v[238:241], v242 offset0:0 offset1:2
	ds_read2_b64 v[234:237], v163 offset0:32 offset1:34
	ds_read_b128 v[172:175], v0 offset:13376
	ds_read_b128 v[176:179], v0 offset:20032
	ds_read_b128 v[180:183], v0 offset:13408
	ds_read_b128 v[184:187], v0 offset:20064
	ds_read_b128 v[188:191], v0 offset:13440
	ds_read_b128 v[192:195], v0 offset:20096
	ds_read_b128 v[196:199], v0 offset:13472
	ds_read_b128 v[220:223], v0 offset:20128
	v_exp_f32_e32 v50, v50
	v_exp_f32_e32 v51, v51
	v_exp_f32_e32 v52, v52
	v_exp_f32_e32 v53, v53
	v_exp_f32_e32 v54, v54
	v_exp_f32_e32 v55, v55
	v_exp_f32_e32 v56, v56
	v_exp_f32_e32 v57, v57
	s_waitcnt lgkmcnt(13)
	v_mfma_f32_32x32x16_bf16 v[82:97], v[82:85], v[122:125], 0
	v_cvt_pk_bf16_f32 v224, v50, v51
	v_cvt_pk_bf16_f32 v225, v52, v53
	v_cvt_pk_bf16_f32 v226, v54, v55
	v_cvt_pk_bf16_f32 v227, v56, v57
	v_exp_f32_e32 v58, v58
	v_add_f32_e32 v200, v50, v51
	s_waitcnt lgkmcnt(12)
	v_mfma_f32_32x32x16_bf16 v[98:113], v[98:101], v[122:125], 0
	v_exp_f32_e32 v59, v59
	v_exp_f32_e32 v60, v60
	v_add_f32_e32 v201, v52, v53
	v_exp_f32_e32 v61, v61
	s_waitcnt lgkmcnt(11)
	v_mfma_f32_32x32x16_bf16 v[82:97], v[164:167], v[126:129], v[82:97]
	v_exp_f32_e32 v62, v62
	v_add_f32_e32 v200, v200, v54
	v_exp_f32_e32 v63, v63
	v_add_f32_e32 v201, v201, v55
	v_exp_f32_e32 v64, v64
	s_waitcnt lgkmcnt(10)
	v_mfma_f32_32x32x16_bf16 v[98:113], v[168:171], v[126:129], v[98:113]
	ds_read2_b64 v[164:167], v242 offset0:4 offset1:6
	ds_read2_b64 v[168:171], v163 offset0:36 offset1:38
	v_add_f32_e32 v200, v200, v56
	v_exp_f32_e32 v65, v65
	v_add_f32_e32 v201, v201, v57
	v_cvt_pk_bf16_f32 v228, v58, v59
	v_cvt_pk_bf16_f32 v229, v60, v61
	s_waitcnt lgkmcnt(11)
	v_mfma_f32_32x32x16_bf16 v[18:33], v[238:241], v[224:227], v[18:33]
	v_cvt_pk_bf16_f32 v230, v62, v63
	v_cvt_pk_bf16_f32 v231, v64, v65
	v_exp_f32_e32 v66, v66
	v_add_f32_e32 v200, v200, v58
	v_exp_f32_e32 v67, v67
	v_add_f32_e32 v201, v201, v59
	s_waitcnt lgkmcnt(10)
	v_mfma_f32_32x32x16_bf16 v[34:49], v[234:237], v[224:227], v[34:49]
	v_exp_f32_e32 v68, v68
	v_add_f32_e32 v200, v200, v60
	v_exp_f32_e32 v69, v69
	v_add_f32_e32 v201, v201, v61
	v_exp_f32_e32 v70, v70
	s_waitcnt lgkmcnt(9)
	v_mfma_f32_32x32x16_bf16 v[82:97], v[172:175], v[134:137], v[82:97]
	v_add_f32_e32 v200, v200, v62
	v_exp_f32_e32 v71, v71
	v_add_f32_e32 v201, v201, v63
	v_exp_f32_e32 v72, v72
	v_add_f32_e32 v200, v200, v64
	s_waitcnt lgkmcnt(8)
	v_mfma_f32_32x32x16_bf16 v[98:113], v[176:179], v[134:137], v[98:113]
	ds_read2_b64 v[172:175], v242 offset0:8 offset1:10
	ds_read2_b64 v[176:179], v163 offset0:40 offset1:42
	v_exp_f32_e32 v73, v73
	v_add_f32_e32 v201, v201, v65
	v_cvt_pk_bf16_f32 v224, v66, v67
	v_cvt_pk_bf16_f32 v225, v68, v69
	v_cvt_pk_bf16_f32 v226, v70, v71
	s_waitcnt lgkmcnt(3)
	v_mfma_f32_32x32x16_bf16 v[18:33], v[164:167], v[228:231], v[18:33]
	v_cvt_pk_bf16_f32 v227, v72, v73
	v_exp_f32_e32 v74, v74
	v_add_f32_e32 v200, v200, v66
	v_exp_f32_e32 v75, v75
	v_add_f32_e32 v201, v201, v67
	s_waitcnt lgkmcnt(2)
	v_mfma_f32_32x32x16_bf16 v[34:49], v[168:171], v[228:231], v[34:49]
	v_exp_f32_e32 v76, v76
	v_add_f32_e32 v200, v200, v68
	v_exp_f32_e32 v77, v77
	v_add_f32_e32 v201, v201, v69
	v_exp_f32_e32 v78, v78
	s_waitcnt lgkmcnt(9)
	v_mfma_f32_32x32x16_bf16 v[82:97], v[180:183], v[138:141], v[82:97]
	v_add_f32_e32 v200, v200, v70
	v_exp_f32_e32 v79, v79
	v_add_f32_e32 v201, v201, v71
	v_exp_f32_e32 v80, v80
	v_add_f32_e32 v200, v200, v72
	s_waitcnt lgkmcnt(8)
	v_mfma_f32_32x32x16_bf16 v[98:113], v[184:187], v[138:141], v[98:113]
	ds_read2_b64 v[180:183], v242 offset0:12 offset1:14
	ds_read2_b64 v[184:187], v163 offset0:44 offset1:46
	v_exp_f32_e32 v81, v81
	v_add_f32_e32 v201, v201, v73
	v_cvt_pk_bf16_f32 v228, v74, v75
	v_cvt_pk_bf16_f32 v229, v76, v77
	v_cvt_pk_bf16_f32 v230, v78, v79
	s_waitcnt lgkmcnt(3)
	v_mfma_f32_32x32x16_bf16 v[18:33], v[172:175], v[224:227], v[18:33]
	v_cvt_pk_bf16_f32 v231, v80, v81
	v_add_f32_e32 v200, v200, v74
	v_add_f32_e32 v201, v201, v75
	v_add_f32_e32 v200, v200, v76
	v_add_f32_e32 v201, v201, v77
	v_add_f32_e32 v200, v200, v78
	v_add_f32_e32 v201, v201, v79
	v_add_f32_e32 v200, v200, v80
	s_waitcnt lgkmcnt(2)
	v_mfma_f32_32x32x16_bf16 v[34:49], v[176:179], v[224:227], v[34:49]
	v_add_f32_e32 v201, v201, v81
	v_add_f32_e32 v200, v200, v201
	v_add_f32_e32 v162, v162, v200
	s_waitcnt lgkmcnt(9)
	v_mfma_f32_32x32x16_bf16 v[82:97], v[188:191], v[142:145], v[82:97]
	s_waitcnt lgkmcnt(8)
	v_mfma_f32_32x32x16_bf16 v[98:113], v[192:195], v[142:145], v[98:113]
	s_waitcnt lgkmcnt(7)
	v_mfma_f32_32x32x16_bf16 v[82:97], v[196:199], v[146:149], v[82:97]
	s_waitcnt lgkmcnt(0)
	v_cndmask_b32_e64 v0, 0, 1, s[44:45]
	v_cmp_ne_u32_e64 s[42:43], 1, v0
	s_andn2_b64 vcc, exec, s[44:45]
	s_cbranch_vccnz .Lt1a_mid
	s_and_b32 s44, s53, 2
	s_mulk_i32 s44, 0x3400
	s_add_i32 s62, s44, 0
	v_add_u32_e32 v0, s62, v151
	s_waitcnt vmcnt(0)
	ds_write_b128 v0, v[118:121]
	s_and_saveexec_b64 s[44:45], s[40:41]
	v_add_u32_e32 v0, s62, v159
	ds_write_b128 v0, v[6:9]
	s_or_b64 exec, exec, s[44:45]

.Lt1a_end:
	v_mfma_f32_32x32x16_bf16 v[98:113], v[220:223], v[146:149], v[98:113]
	v_mfma_f32_32x32x16_bf16 v[18:33], v[180:183], v[228:231], v[18:33]
	v_mfma_f32_32x32x16_bf16 v[34:49], v[184:187], v[228:231], v[34:49]
	s_branch .LBB0_556

.LBB0_563:
	s_cmp_ge_u32 s52, s51
	s_mul_i32 s58, s25, 0x2200
	s_cbranch_scc1 .LBB0_565
	s_andn2_b32 s52, 2, s52
	s_mulk_i32 s52, 0x3400
	v_add_u32_e32 v0, s52, v160
	v_add_u32_e32 v242, s58, v161
	v_add_u32_e32 v163, 0xe000, v242
	v_add_u32_e32 v242, 0xd000, v242
	ds_read_b128 v[50:53], v0 offset:0
	ds_read_b128 v[66:69], v0 offset:6656
	ds_read_b128 v[164:167], v0 offset:32
	ds_read_b128 v[168:171], v0 offset:6688
	ds_read2_b64 v[238:241], v242 offset0:0 offset1:2
	ds_read2_b64 v[234:237], v163 offset0:32 offset1:34
	ds_read_b128 v[172:175], v0 offset:64
	ds_read_b128 v[176:179], v0 offset:6720
	ds_read_b128 v[180:183], v0 offset:96
	ds_read_b128 v[184:187], v0 offset:6752
	ds_read_b128 v[188:191], v0 offset:128
	ds_read_b128 v[192:195], v0 offset:6784
	ds_read_b128 v[196:199], v0 offset:160
	ds_read_b128 v[220:223], v0 offset:6816
	v_exp_f32_e32 v82, v82
	v_exp_f32_e32 v83, v83
	v_exp_f32_e32 v84, v84
	v_exp_f32_e32 v85, v85
	v_exp_f32_e32 v86, v86
	v_exp_f32_e32 v87, v87
	v_exp_f32_e32 v88, v88
	v_exp_f32_e32 v89, v89
	s_waitcnt lgkmcnt(13)
	v_mfma_f32_32x32x16_bf16 v[50:65], v[50:53], v[122:125], 0
	v_cvt_pk_bf16_f32 v224, v82, v83
	v_cvt_pk_bf16_f32 v225, v84, v85
	v_cvt_pk_bf16_f32 v226, v86, v87
	v_cvt_pk_bf16_f32 v227, v88, v89
	v_exp_f32_e32 v90, v90
	v_add_f32_e32 v200, v82, v83
	s_waitcnt lgkmcnt(12)
	v_mfma_f32_32x32x16_bf16 v[66:81], v[66:69], v[122:125], 0
	v_exp_f32_e32 v91, v91
	v_exp_f32_e32 v92, v92
	v_add_f32_e32 v201, v84, v85
	v_exp_f32_e32 v93, v93
	s_waitcnt lgkmcnt(11)
	v_mfma_f32_32x32x16_bf16 v[50:65], v[164:167], v[126:129], v[50:65]
	v_exp_f32_e32 v94, v94
	v_add_f32_e32 v200, v200, v86
	v_exp_f32_e32 v95, v95
	v_add_f32_e32 v201, v201, v87
	v_exp_f32_e32 v96, v96
	s_waitcnt lgkmcnt(10)
	v_mfma_f32_32x32x16_bf16 v[66:81], v[168:171], v[126:129], v[66:81]
	ds_read2_b64 v[164:167], v242 offset0:4 offset1:6
	ds_read2_b64 v[168:171], v163 offset0:36 offset1:38
	v_add_f32_e32 v200, v200, v88
	v_exp_f32_e32 v97, v97
	v_add_f32_e32 v201, v201, v89
	v_cvt_pk_bf16_f32 v228, v90, v91
	v_cvt_pk_bf16_f32 v229, v92, v93
	s_waitcnt lgkmcnt(11)
	v_mfma_f32_32x32x16_bf16 v[18:33], v[238:241], v[224:227], v[18:33]
	v_cvt_pk_bf16_f32 v230, v94, v95
	v_cvt_pk_bf16_f32 v231, v96, v97
	v_exp_f32_e32 v98, v98
	v_add_f32_e32 v200, v200, v90
	v_exp_f32_e32 v99, v99
	v_add_f32_e32 v201, v201, v91
	s_waitcnt lgkmcnt(10)
	v_mfma_f32_32x32x16_bf16 v[34:49], v[234:237], v[224:227], v[34:49]
	v_exp_f32_e32 v100, v100
	v_add_f32_e32 v200, v200, v92
	v_exp_f32_e32 v101, v101
	v_add_f32_e32 v201, v201, v93
	v_exp_f32_e32 v102, v102
	s_waitcnt lgkmcnt(9)
	v_mfma_f32_32x32x16_bf16 v[50:65], v[172:175], v[134:137], v[50:65]
	v_add_f32_e32 v200, v200, v94
	v_exp_f32_e32 v103, v103
	v_add_f32_e32 v201, v201, v95
	v_exp_f32_e32 v104, v104
	v_add_f32_e32 v200, v200, v96
	s_waitcnt lgkmcnt(8)
	v_mfma_f32_32x32x16_bf16 v[66:81], v[176:179], v[134:137], v[66:81]
	ds_read2_b64 v[172:175], v242 offset0:8 offset1:10
	ds_read2_b64 v[176:179], v163 offset0:40 offset1:42
	v_exp_f32_e32 v105, v105
	v_add_f32_e32 v201, v201, v97
	v_cvt_pk_bf16_f32 v224, v98, v99
	v_cvt_pk_bf16_f32 v225, v100, v101
	v_cvt_pk_bf16_f32 v226, v102, v103
	s_waitcnt lgkmcnt(3)
	v_mfma_f32_32x32x16_bf16 v[18:33], v[164:167], v[228:231], v[18:33]
	v_cvt_pk_bf16_f32 v227, v104, v105
	v_exp_f32_e32 v106, v106
	v_add_f32_e32 v200, v200, v98
	v_exp_f32_e32 v107, v107
	v_add_f32_e32 v201, v201, v99
	s_waitcnt lgkmcnt(2)
	v_mfma_f32_32x32x16_bf16 v[34:49], v[168:171], v[228:231], v[34:49]
	v_exp_f32_e32 v108, v108
	v_add_f32_e32 v200, v200, v100
	v_exp_f32_e32 v109, v109
	v_add_f32_e32 v201, v201, v101
	v_exp_f32_e32 v110, v110
	s_waitcnt lgkmcnt(9)
	v_mfma_f32_32x32x16_bf16 v[50:65], v[180:183], v[138:141], v[50:65]
	v_add_f32_e32 v200, v200, v102
	v_exp_f32_e32 v111, v111
	v_add_f32_e32 v201, v201, v103
	v_exp_f32_e32 v112, v112
	v_add_f32_e32 v200, v200, v104
	s_waitcnt lgkmcnt(8)
	v_mfma_f32_32x32x16_bf16 v[66:81], v[184:187], v[138:141], v[66:81]
	ds_read2_b64 v[180:183], v242 offset0:12 offset1:14
	ds_read2_b64 v[184:187], v163 offset0:44 offset1:46
	v_exp_f32_e32 v113, v113
	v_add_f32_e32 v201, v201, v105
	v_cvt_pk_bf16_f32 v228, v106, v107
	v_cvt_pk_bf16_f32 v229, v108, v109
	v_cvt_pk_bf16_f32 v230, v110, v111
	s_waitcnt lgkmcnt(3)
	v_mfma_f32_32x32x16_bf16 v[18:33], v[172:175], v[224:227], v[18:33]
	v_cvt_pk_bf16_f32 v231, v112, v113
	v_add_f32_e32 v200, v200, v106
	v_add_f32_e32 v201, v201, v107
	v_add_f32_e32 v200, v200, v108
	v_add_f32_e32 v201, v201, v109
	v_add_f32_e32 v200, v200, v110
	v_add_f32_e32 v201, v201, v111
	v_add_f32_e32 v200, v200, v112
	s_waitcnt lgkmcnt(2)
	v_mfma_f32_32x32x16_bf16 v[34:49], v[176:179], v[224:227], v[34:49]
	v_add_f32_e32 v201, v201, v113
	v_add_f32_e32 v200, v200, v201
	v_add_f32_e32 v162, v162, v200
	s_waitcnt lgkmcnt(9)
	v_mfma_f32_32x32x16_bf16 v[50:65], v[188:191], v[142:145], v[50:65]
	s_waitcnt lgkmcnt(8)
	v_mfma_f32_32x32x16_bf16 v[66:81], v[192:195], v[142:145], v[66:81]
	s_waitcnt lgkmcnt(7)
	v_mfma_f32_32x32x16_bf16 v[50:65], v[196:199], v[146:149], v[50:65]
	s_waitcnt lgkmcnt(0)
	s_and_b64 vcc, exec, s[44:45]
	s_cbranch_vccnz .Lt2a_mid
	s_and_b32 s44, s60, 3
	s_mulk_i32 s44, 0x3400
	s_add_i32 s52, s44, 0
	v_add_u32_e32 v0, s52, v151
	s_waitcnt vmcnt(0)
	ds_write_b128 v0, v[2:5]
	s_and_saveexec_b64 s[44:45], s[40:41]
	v_add_u32_e32 v0, s52, v159
	ds_write_b128 v0, v[10:13]
	s_or_b64 exec, exec, s[44:45]

.Lt2a_end:
	v_mfma_f32_32x32x16_bf16 v[66:81], v[220:223], v[146:149], v[66:81]
	v_mfma_f32_32x32x16_bf16 v[18:33], v[180:183], v[228:231], v[18:33]
	v_mfma_f32_32x32x16_bf16 v[34:49], v[184:187], v[228:231], v[34:49]
	s_branch .LBB0_571
